# plus: phase 9 tile-slot permutation (N-tile slots 4,5 swapped with 6,7) balancing 40/28 k-iterations per workgroup to 36/32
# speedup vs baseline: 1.0137x; 1.0034x over previous
;   DI bf16_t* wt_uq() const { return (bf16_t*)(ws + OFF_WT_UQ); }
;   DI bf16_t* wt_ukv() const { return (bf16_t*)(ws + OFF_WT_UKV); }
;   DI bf16_t* z() const { return (bf16_t*)(ws + OFF_Z); }
; DI GTile up_tile(const Params& p, int t) {
;   const int mt = t & 63, nt = t >> 6;
;   if (nt < 6) return GTile{p.z(), LDZ1, p.wt_uq(), 768, 768, mt * 256, nt * 256};
;   return GTile{p.z() + 768, LDZ1, p.wt_ukv(), 512, 512, mt * 256, (nt - 6) * 256};
; }
; DI void phase_up(const Params& p, char* smem) {
;   float* rs = (float*)(smem + G_RSTD_OFF);
;   u32x4 ra[4], rb[4]; bool pre = false;
;   int rs_key = -1;
;   for (int t = blockIdx.x; t < 64 * 14; t += gridDim.x) {
;     const int mt = t & 63, nt = t >> 6, tn = t + gridDim.x;
;     const bool has_next = tn < 64 * 14;
;     const GTile tl = up_tile(p, t), nx = up_tile(p, has_next ? tn : t);
.LBB0_972:
	s_ashr_i32 s89, s16, 6
	s_and_b32 s98, s89, 0xfffffffc
	s_cmp_eq_u32 s98, 4
	s_cselect_b32 s98, 2, 0
	s_xor_b32 s89, s89, s98
	s_cmp_lt_i32 s89, 6
	s_cselect_b64 s[50:51], -1, 0
	s_cmp_gt_i32 s89, 5
	s_cselect_b64 s[6:7], -1, 0
	s_lshl_b32 s79, s89, 8
	s_movk_i32 s80, 0x300
	s_and_b64 vcc, exec, s[50:51]
	s_mov_b64 s[72:73], s[12:13]
	s_mov_b64 s[74:75], s[10:11]
	s_movk_i32 s84, 0x300
	s_mov_b32 s70, s79
	s_cbranch_vccnz .LBB0_974
	s_add_i32 s70, s79, 0xfffffa00
	s_movk_i32 s84, 0x200
	s_mov_b64 s[72:73], s[8:9]
	s_mov_b64 s[74:75], s[0:1]
.LBB0_974:
	s_add_i32 s63, s16, s96
	s_cmpk_gt_i32 s63, 0x37f
	s_cselect_b64 s[52:53], -1, 0
	s_cmpk_lt_i32 s63, 0x380
	s_cselect_b64 s[54:55], -1, 0
	s_and_b64 s[18:19], s[54:55], exec
	s_cselect_b32 s17, s63, s16
	s_ashr_i32 s18, s17, 6
	s_and_b32 s98, s18, 0xfffffffc
	s_cmp_eq_u32 s98, 4
	s_cselect_b32 s98, 2, 0
	s_xor_b32 s18, s18, s98
	s_lshl_b32 s82, s18, 8
	s_cmp_lt_i32 s18, 6
	s_cbranch_scc1 .LBB0_976
	s_addk_i32 s82, 0xfa00
	s_movk_i32 s80, 0x200
	s_mov_b64 s[66:67], s[8:9]
	s_mov_b64 s[68:69], s[0:1]
	s_branch .LBB0_977
